# speedup vs baseline: 1.0007x; 1.0007x over previous
; template <int MODE>
; DEV void gemm_phase(const bf16_t* __restrict__ A, const bf16_t* __restrict__ Bt, int M, int N, int K, bf16_t* __restrict__ Out, int ldo,
;                     const float* __restrict__ rstd, const float* __restrict__ rope) {
;     ...
;       const bool ropet = (MODE == G_INPROJ) && (pn >= 12 && pn < 20) && ((wc & 1) == 0);
; #pragma unroll
;       for (int ai = 0; ai < 2; ++ai)
; #pragma unroll
;         for (int m = 0; m < 4; ++m) {
;           const int row = brow + ai * HALF + wr * 64 + m * 16 + fr;
;           float rs = 1.f; if constexpr (MODE == G_INPROJ) rs = rstd[row];
; #pragma unroll
;           for (int bj = 0; bj < 2; ++bj) {
;             f32x4 v0 = acc[ai][bj][m][0], v1 = acc[ai][bj][m][1];
;             if constexpr (MODE == G_INPROJ) {
;               if (ropet) {
;                 const f32x4 c0 = *reinterpret_cast<const f32x4*>(rope + (size_t)row * 16), c1 = *reinterpret_cast<const f32x4*>(rope + (size_t)row * 16 + 4);
;                 const f32x4 s0 = *reinterpret_cast<const f32x4*>(rope + (size_t)row * 16 + 8), s1 = *reinterpret_cast<const f32x4*>(rope + (size_t)row * 16 + 12);
.LBB0_131:
	v_lshl_add_u32 v164, s41, 8, v170
	v_ashrrev_i32_e32 v165, 31, v164
	v_lshl_add_u64 v[128:129], v[164:165], 2, s[68:69]
	v_mov_b32_e32 v194, v232
	v_mov_b32_e32 v196, v234
	v_mov_b32_e32 v198, v236
	v_mov_b32_e32 v200, v238
	v_mov_b32_e32 v202, v240
	v_mov_b32_e32 v204, v242
	v_mov_b32_e32 v206, v244
	v_mov_b32_e32 v208, v246
	s_add_i32 s8, s40, -12
	s_cmp_lt_u32 s8, 8
	s_cselect_b64 s[8:9], -1, 0
	s_and_b64 s[26:27], s[8:9], s[14:15]
	v_lshlrev_b64 v[128:129], 6, v[164:165]
	v_lshl_add_u64 v[168:169], s[72:73], 0, v[128:129]
	s_and_b64 vcc, exec, s[26:27]
	s_cbranch_vccz .LBB0_141
	global_load_dwordx4 v[132:135], v[168:169], off offset:48
	global_load_dwordx4 v[144:147], v[168:169], off offset:32
	global_load_dwordx4 v[128:131], v[168:169], off offset:16
	global_load_dwordx4 v[136:139], v[168:169], off
	global_load_dword v226, v[168:169], off offset:1024
	global_load_dword v227, v[168:169], off offset:2048
	global_load_dword v228, v[168:169], off offset:3072
	v_add_co_u32_e32 v250, vcc, 0x2000, v168
	s_nop 1
	v_addc_co_u32_e32 v251, vcc, 0, v169, vcc
	global_load_dword v229, v[250:251], off
	global_load_dword v230, v[250:251], off offset:1024
	global_load_dword v231, v[250:251], off offset:2048
	global_load_dword v233, v[250:251], off offset:3072
	v_and_b32_e32 v141, 64, v211
	v_xor_b32_e32 v140, 16, v211
	v_add_u32_e32 v141, 64, v141
	v_cmp_lt_i32_e32 vcc, v140, v141
	v_mov_b64_e32 v[150:151], v[122:123]
	v_mov_b64_e32 v[148:149], v[120:121]
	v_cndmask_b32_e32 v140, v211, v140, vcc
	v_lshlrev_b32_e32 v165, 2, v140
	ds_bpermute_b32 v173, v165, v124
	ds_bpermute_b32 v167, v165, v120
	v_mov_b64_e32 v[142:143], v[126:127]
	v_mov_b64_e32 v[140:141], v[124:125]
	s_and_saveexec_b64 s[8:9], s[4:5]
	s_cbranch_execz .LBB0_134
	s_waitcnt vmcnt(0) lgkmcnt(0)
	v_mul_f32_e32 v140, v144, v173
	v_cndmask_b32_e64 v144, v140, -v140, s[6:7]
	v_mov_b64_e32 v[142:143], v[126:127]
	v_fmac_f32_e32 v144, v124, v136
	v_mov_b64_e32 v[140:141], v[124:125]
	v_mul_f32_e32 v124, v132, v167
	v_cndmask_b32_e64 v124, v124, -v124, s[6:7]
	v_mov_b64_e32 v[150:151], v[122:123]
	v_fmac_f32_e32 v124, v120, v128
	v_mov_b64_e32 v[148:149], v[120:121]
	v_mov_b32_e32 v140, v144
	v_mov_b32_e32 v148, v124
